# phase 0 DFT-weight table: per-wave twiddle table in LDS (same v_sin/v_cos bits), wave-uniform weights fetched once per wave and broadcast with v_readlane, same summation order
# speedup vs baseline: 1.0085x; 1.0047x over previous
; __device__ __forceinline__ void phase0(const Params& p, LAS unsigned char* lds) {
;     ...
;     for (int i = gt; i < 4 * 128 * 256; i += NGT) {
;         const int k = i & 255, e = (i >> 8) & 127, g = i >> 15, d = k & 127; const bool sn = k >= 128;
;         float s = 0.f;
;         for (int dp = 0; dp < 128; ++dp) { const float fr = (float)((d * dp) & 127) * (1.f / 128.f);
;             const float tw = sn ? __builtin_amdgcn_sinf(fr) : __builtin_amdgcn_cosf(fr);
;             s += tw * wf[(g * 128 + dp) * 128 + e]; }
;         CWT[i] = (h16)(s * 0.08838834764831845f);
.LBB0_126:
	v_and_b32_e32 v10, 0x80, v0
	v_bfe_u32 v9, v0, 8, 7
	v_cmp_eq_u32_e32 vcc, 0, v10
	v_ashrrev_i32_e32 v10, 15, v0
	v_lshl_or_b32 v9, v10, 14, v9
	v_and_b32_e32 v11, 63, v0
	v_bfe_u32 v12, v0, 6, 3
	v_lshlrev_b32_e32 v12, 9, v12
	v_add_u32_e32 v12, 0x11000, v12
	v_add_u32_e32 v13, 64, v11
	v_cvt_f32_ubyte0_e32 v14, v11
	v_cvt_f32_ubyte0_e32 v15, v13
	v_mul_f32_e32 v14, 0x3c000000, v14
	v_mul_f32_e32 v15, 0x3c000000, v15
	v_sin_f32_e32 v16, v14
	v_cos_f32_e32 v17, v14
	v_sin_f32_e32 v18, v15
	v_cos_f32_e32 v19, v15
	v_lshl_add_u32 v20, v11, 7, v9
	v_mov_b32_e32 v21, 0
	v_lshl_add_u64 v[22:23], v[20:21], 2, s[46:47]
	v_add_u32_e32 v20, 0x2000, v20
	v_lshl_add_u64 v[24:25], v[20:21], 2, s[46:47]
	global_load_dword v26, v[22:23], off
	global_load_dword v27, v[24:25], off
	s_nop 1
	v_cndmask_b32_e32 v16, v16, v17, vcc
	v_cndmask_b32_e32 v18, v18, v19, vcc
	v_lshl_add_u32 v13, v11, 2, v12
	ds_write_b32 v13, v16
	ds_write_b32 v13, v18 offset:256
	v_and_b32_e32 v1, 0x7f, v0
	v_lshlrev_b32_e32 v1, 2, v1
	v_mov_b32_e32 v11, 0
	v_mov_b32_e32 v10, 0
	s_movk_i32 s28, 0x1fc
	s_waitcnt vmcnt(0) lgkmcnt(0)
	v_and_or_b32 v13, v11, s28, v12
	v_add_u32_e32 v11, v11, v1
	v_and_or_b32 v14, v11, s28, v12
	v_add_u32_e32 v11, v11, v1
	v_and_or_b32 v15, v11, s28, v12
	v_add_u32_e32 v11, v11, v1
	v_and_or_b32 v16, v11, s28, v12
	v_add_u32_e32 v11, v11, v1
	v_and_or_b32 v17, v11, s28, v12
	v_add_u32_e32 v11, v11, v1
	v_and_or_b32 v18, v11, s28, v12
	v_add_u32_e32 v11, v11, v1
	v_and_or_b32 v19, v11, s28, v12
	v_add_u32_e32 v11, v11, v1
	v_and_or_b32 v20, v11, s28, v12
	v_add_u32_e32 v11, v11, v1
	ds_read_b32 v13, v13
	ds_read_b32 v14, v14
	ds_read_b32 v15, v15
	ds_read_b32 v16, v16
	ds_read_b32 v17, v17
	ds_read_b32 v18, v18
	ds_read_b32 v19, v19
	ds_read_b32 v20, v20
	v_and_or_b32 v21, v11, s28, v12
	v_add_u32_e32 v11, v11, v1
	v_and_or_b32 v22, v11, s28, v12
	v_add_u32_e32 v11, v11, v1
	v_and_or_b32 v23, v11, s28, v12
	v_add_u32_e32 v11, v11, v1
	v_and_or_b32 v24, v11, s28, v12
	v_add_u32_e32 v11, v11, v1
	v_and_or_b32 v25, v11, s28, v12
	v_add_u32_e32 v11, v11, v1
	v_and_or_b32 v28, v11, s28, v12
	v_add_u32_e32 v11, v11, v1
	v_and_or_b32 v29, v11, s28, v12
	v_add_u32_e32 v11, v11, v1
	v_and_or_b32 v30, v11, s28, v12
	v_add_u32_e32 v11, v11, v1
	ds_read_b32 v21, v21
	ds_read_b32 v22, v22
	ds_read_b32 v23, v23
	ds_read_b32 v24, v24
	ds_read_b32 v25, v25
	ds_read_b32 v28, v28
	ds_read_b32 v29, v29
	ds_read_b32 v30, v30
	s_waitcnt lgkmcnt(8)
	v_readlane_b32 s9, v26, 0
	v_fmac_f32_e32 v10, s9, v13
	v_readlane_b32 s12, v26, 1
	v_fmac_f32_e32 v10, s12, v14
	v_readlane_b32 s9, v26, 2
	v_fmac_f32_e32 v10, s9, v15
	v_readlane_b32 s12, v26, 3
	v_fmac_f32_e32 v10, s12, v16
	v_readlane_b32 s9, v26, 4
	v_fmac_f32_e32 v10, s9, v17
	v_readlane_b32 s12, v26, 5
	v_fmac_f32_e32 v10, s12, v18
	v_readlane_b32 s9, v26, 6
	v_fmac_f32_e32 v10, s9, v19
	v_readlane_b32 s12, v26, 7
	v_fmac_f32_e32 v10, s12, v20
	v_and_or_b32 v13, v11, s28, v12
	v_add_u32_e32 v11, v11, v1
	v_and_or_b32 v14, v11, s28, v12
	v_add_u32_e32 v11, v11, v1
	v_and_or_b32 v15, v11, s28, v12
	v_add_u32_e32 v11, v11, v1
	v_and_or_b32 v16, v11, s28, v12
	v_add_u32_e32 v11, v11, v1
	v_and_or_b32 v17, v11, s28, v12
	v_add_u32_e32 v11, v11, v1
	v_and_or_b32 v18, v11, s28, v12
	v_add_u32_e32 v11, v11, v1
	v_and_or_b32 v19, v11, s28, v12
	v_add_u32_e32 v11, v11, v1
	v_and_or_b32 v20, v11, s28, v12
	v_add_u32_e32 v11, v11, v1
	ds_read_b32 v13, v13
	ds_read_b32 v14, v14
	ds_read_b32 v15, v15
	ds_read_b32 v16, v16
	ds_read_b32 v17, v17
	ds_read_b32 v18, v18
	ds_read_b32 v19, v19
	ds_read_b32 v20, v20
	s_waitcnt lgkmcnt(8)
	v_readlane_b32 s9, v26, 8
	v_fmac_f32_e32 v10, s9, v21
	v_readlane_b32 s12, v26, 9
	v_fmac_f32_e32 v10, s12, v22
	v_readlane_b32 s9, v26, 10
	v_fmac_f32_e32 v10, s9, v23
	v_readlane_b32 s12, v26, 11
	v_fmac_f32_e32 v10, s12, v24
	v_readlane_b32 s9, v26, 12
	v_fmac_f32_e32 v10, s9, v25
	v_readlane_b32 s12, v26, 13
	v_fmac_f32_e32 v10, s12, v28
	v_readlane_b32 s9, v26, 14
	v_fmac_f32_e32 v10, s9, v29
	v_readlane_b32 s12, v26, 15
	v_fmac_f32_e32 v10, s12, v30
	v_and_or_b32 v21, v11, s28, v12
	v_add_u32_e32 v11, v11, v1
	v_and_or_b32 v22, v11, s28, v12
	v_add_u32_e32 v11, v11, v1
	v_and_or_b32 v23, v11, s28, v12
	v_add_u32_e32 v11, v11, v1
	v_and_or_b32 v24, v11, s28, v12
	v_add_u32_e32 v11, v11, v1
	v_and_or_b32 v25, v11, s28, v12
	v_add_u32_e32 v11, v11, v1
	v_and_or_b32 v28, v11, s28, v12
	v_add_u32_e32 v11, v11, v1
	v_and_or_b32 v29, v11, s28, v12
	v_add_u32_e32 v11, v11, v1
	v_and_or_b32 v30, v11, s28, v12
	v_add_u32_e32 v11, v11, v1
	ds_read_b32 v21, v21
	ds_read_b32 v22, v22
	ds_read_b32 v23, v23
	ds_read_b32 v24, v24
	ds_read_b32 v25, v25
	ds_read_b32 v28, v28
	ds_read_b32 v29, v29
	ds_read_b32 v30, v30
	s_waitcnt lgkmcnt(8)
	v_readlane_b32 s9, v26, 16
	v_fmac_f32_e32 v10, s9, v13
	v_readlane_b32 s12, v26, 17
	v_fmac_f32_e32 v10, s12, v14
	v_readlane_b32 s9, v26, 18
	v_fmac_f32_e32 v10, s9, v15
	v_readlane_b32 s12, v26, 19
	v_fmac_f32_e32 v10, s12, v16
	v_readlane_b32 s9, v26, 20
	v_fmac_f32_e32 v10, s9, v17
	v_readlane_b32 s12, v26, 21
	v_fmac_f32_e32 v10, s12, v18
	v_readlane_b32 s9, v26, 22
	v_fmac_f32_e32 v10, s9, v19
	v_readlane_b32 s12, v26, 23
	v_fmac_f32_e32 v10, s12, v20
	v_and_or_b32 v13, v11, s28, v12
	v_add_u32_e32 v11, v11, v1
	v_and_or_b32 v14, v11, s28, v12
	v_add_u32_e32 v11, v11, v1
	v_and_or_b32 v15, v11, s28, v12
	v_add_u32_e32 v11, v11, v1
	v_and_or_b32 v16, v11, s28, v12
	v_add_u32_e32 v11, v11, v1
	v_and_or_b32 v17, v11, s28, v12
	v_add_u32_e32 v11, v11, v1
	v_and_or_b32 v18, v11, s28, v12
	v_add_u32_e32 v11, v11, v1
	v_and_or_b32 v19, v11, s28, v12
	v_add_u32_e32 v11, v11, v1
	v_and_or_b32 v20, v11, s28, v12
	v_add_u32_e32 v11, v11, v1
	ds_read_b32 v13, v13
	ds_read_b32 v14, v14
	ds_read_b32 v15, v15
	ds_read_b32 v16, v16
	ds_read_b32 v17, v17
	ds_read_b32 v18, v18
	ds_read_b32 v19, v19
	ds_read_b32 v20, v20
	s_waitcnt lgkmcnt(8)
; __device__ __forceinline__ void phase0(const Params& p, LAS unsigned char* lds) {
;     ...
;     for (int i = gt; i < 4 * 128 * 256; i += NGT) {
;         const int k = i & 255, e = (i >> 8) & 127, g = i >> 15, d = k & 127; const bool sn = k >= 128;
;         float s = 0.f;
;         for (int dp = 0; dp < 128; ++dp) { const float fr = (float)((d * dp) & 127) * (1.f / 128.f);
;             const float tw = sn ? __builtin_amdgcn_sinf(fr) : __builtin_amdgcn_cosf(fr);
;             s += tw * wf[(g * 128 + dp) * 128 + e]; }
;         CWT[i] = (h16)(s * 0.08838834764831845f);
	v_readlane_b32 s9, v26, 24
	v_fmac_f32_e32 v10, s9, v21
	v_readlane_b32 s12, v26, 25
	v_fmac_f32_e32 v10, s12, v22
	v_readlane_b32 s9, v26, 26
	v_fmac_f32_e32 v10, s9, v23
	v_readlane_b32 s12, v26, 27
	v_fmac_f32_e32 v10, s12, v24
	v_readlane_b32 s9, v26, 28
	v_fmac_f32_e32 v10, s9, v25
	v_readlane_b32 s12, v26, 29
	v_fmac_f32_e32 v10, s12, v28
	v_readlane_b32 s9, v26, 30
	v_fmac_f32_e32 v10, s9, v29
	v_readlane_b32 s12, v26, 31
	v_fmac_f32_e32 v10, s12, v30
	v_and_or_b32 v21, v11, s28, v12
	v_add_u32_e32 v11, v11, v1
	v_and_or_b32 v22, v11, s28, v12
	v_add_u32_e32 v11, v11, v1
	v_and_or_b32 v23, v11, s28, v12
	v_add_u32_e32 v11, v11, v1
	v_and_or_b32 v24, v11, s28, v12
	v_add_u32_e32 v11, v11, v1
	v_and_or_b32 v25, v11, s28, v12
	v_add_u32_e32 v11, v11, v1
	v_and_or_b32 v28, v11, s28, v12
	v_add_u32_e32 v11, v11, v1
	v_and_or_b32 v29, v11, s28, v12
	v_add_u32_e32 v11, v11, v1
	v_and_or_b32 v30, v11, s28, v12
	v_add_u32_e32 v11, v11, v1
	ds_read_b32 v21, v21
	ds_read_b32 v22, v22
	ds_read_b32 v23, v23
	ds_read_b32 v24, v24
	ds_read_b32 v25, v25
	ds_read_b32 v28, v28
	ds_read_b32 v29, v29
	ds_read_b32 v30, v30
	s_waitcnt lgkmcnt(8)
	v_readlane_b32 s9, v26, 32
	v_fmac_f32_e32 v10, s9, v13
	v_readlane_b32 s12, v26, 33
	v_fmac_f32_e32 v10, s12, v14
	v_readlane_b32 s9, v26, 34
	v_fmac_f32_e32 v10, s9, v15
	v_readlane_b32 s12, v26, 35
	v_fmac_f32_e32 v10, s12, v16
	v_readlane_b32 s9, v26, 36
	v_fmac_f32_e32 v10, s9, v17
	v_readlane_b32 s12, v26, 37
	v_fmac_f32_e32 v10, s12, v18
	v_readlane_b32 s9, v26, 38
	v_fmac_f32_e32 v10, s9, v19
	v_readlane_b32 s12, v26, 39
	v_fmac_f32_e32 v10, s12, v20
	v_and_or_b32 v13, v11, s28, v12
	v_add_u32_e32 v11, v11, v1
	v_and_or_b32 v14, v11, s28, v12
	v_add_u32_e32 v11, v11, v1
	v_and_or_b32 v15, v11, s28, v12
	v_add_u32_e32 v11, v11, v1
	v_and_or_b32 v16, v11, s28, v12
	v_add_u32_e32 v11, v11, v1
	v_and_or_b32 v17, v11, s28, v12
	v_add_u32_e32 v11, v11, v1
	v_and_or_b32 v18, v11, s28, v12
	v_add_u32_e32 v11, v11, v1
	v_and_or_b32 v19, v11, s28, v12
	v_add_u32_e32 v11, v11, v1
	v_and_or_b32 v20, v11, s28, v12
	v_add_u32_e32 v11, v11, v1
	ds_read_b32 v13, v13
	ds_read_b32 v14, v14
	ds_read_b32 v15, v15
	ds_read_b32 v16, v16
	ds_read_b32 v17, v17
	ds_read_b32 v18, v18
	ds_read_b32 v19, v19
	ds_read_b32 v20, v20
	s_waitcnt lgkmcnt(8)
	v_readlane_b32 s9, v26, 40
	v_fmac_f32_e32 v10, s9, v21
	v_readlane_b32 s12, v26, 41
	v_fmac_f32_e32 v10, s12, v22
	v_readlane_b32 s9, v26, 42
	v_fmac_f32_e32 v10, s9, v23
	v_readlane_b32 s12, v26, 43
	v_fmac_f32_e32 v10, s12, v24
	v_readlane_b32 s9, v26, 44
	v_fmac_f32_e32 v10, s9, v25
	v_readlane_b32 s12, v26, 45
	v_fmac_f32_e32 v10, s12, v28
	v_readlane_b32 s9, v26, 46
	v_fmac_f32_e32 v10, s9, v29
	v_readlane_b32 s12, v26, 47
	v_fmac_f32_e32 v10, s12, v30
	v_and_or_b32 v21, v11, s28, v12
	v_add_u32_e32 v11, v11, v1
	v_and_or_b32 v22, v11, s28, v12
	v_add_u32_e32 v11, v11, v1
	v_and_or_b32 v23, v11, s28, v12
	v_add_u32_e32 v11, v11, v1
	v_and_or_b32 v24, v11, s28, v12
	v_add_u32_e32 v11, v11, v1
	v_and_or_b32 v25, v11, s28, v12
	v_add_u32_e32 v11, v11, v1
	v_and_or_b32 v28, v11, s28, v12
	v_add_u32_e32 v11, v11, v1
	v_and_or_b32 v29, v11, s28, v12
	v_add_u32_e32 v11, v11, v1
	v_and_or_b32 v30, v11, s28, v12
	v_add_u32_e32 v11, v11, v1
	ds_read_b32 v21, v21
	ds_read_b32 v22, v22
	ds_read_b32 v23, v23
	ds_read_b32 v24, v24
	ds_read_b32 v25, v25
	ds_read_b32 v28, v28
	ds_read_b32 v29, v29
	ds_read_b32 v30, v30
	s_waitcnt lgkmcnt(8)
	v_readlane_b32 s9, v26, 48
	v_fmac_f32_e32 v10, s9, v13
	v_readlane_b32 s12, v26, 49
	v_fmac_f32_e32 v10, s12, v14
	v_readlane_b32 s9, v26, 50
	v_fmac_f32_e32 v10, s9, v15
	v_readlane_b32 s12, v26, 51
	v_fmac_f32_e32 v10, s12, v16
	v_readlane_b32 s9, v26, 52
	v_fmac_f32_e32 v10, s9, v17
	v_readlane_b32 s12, v26, 53
	v_fmac_f32_e32 v10, s12, v18
	v_readlane_b32 s9, v26, 54
	v_fmac_f32_e32 v10, s9, v19
	v_readlane_b32 s12, v26, 55
	v_fmac_f32_e32 v10, s12, v20
	v_and_or_b32 v13, v11, s28, v12
	v_add_u32_e32 v11, v11, v1
	v_and_or_b32 v14, v11, s28, v12
	v_add_u32_e32 v11, v11, v1
	v_and_or_b32 v15, v11, s28, v12
	v_add_u32_e32 v11, v11, v1
	v_and_or_b32 v16, v11, s28, v12
	v_add_u32_e32 v11, v11, v1
	v_and_or_b32 v17, v11, s28, v12
	v_add_u32_e32 v11, v11, v1
	v_and_or_b32 v18, v11, s28, v12
	v_add_u32_e32 v11, v11, v1
	v_and_or_b32 v19, v11, s28, v12
	v_add_u32_e32 v11, v11, v1
	v_and_or_b32 v20, v11, s28, v12
	v_add_u32_e32 v11, v11, v1
	ds_read_b32 v13, v13
	ds_read_b32 v14, v14
	ds_read_b32 v15, v15
	ds_read_b32 v16, v16
	ds_read_b32 v17, v17
	ds_read_b32 v18, v18
	ds_read_b32 v19, v19
	ds_read_b32 v20, v20
	s_waitcnt lgkmcnt(8)
	v_readlane_b32 s9, v26, 56
	v_fmac_f32_e32 v10, s9, v21
	v_readlane_b32 s12, v26, 57
	v_fmac_f32_e32 v10, s12, v22
	v_readlane_b32 s9, v26, 58
	v_fmac_f32_e32 v10, s9, v23
	v_readlane_b32 s12, v26, 59
	v_fmac_f32_e32 v10, s12, v24
	v_readlane_b32 s9, v26, 60
	v_fmac_f32_e32 v10, s9, v25
	v_readlane_b32 s12, v26, 61
	v_fmac_f32_e32 v10, s12, v28
	v_readlane_b32 s9, v26, 62
	v_fmac_f32_e32 v10, s9, v29
	v_readlane_b32 s12, v26, 63
	v_fmac_f32_e32 v10, s12, v30
	v_and_or_b32 v21, v11, s28, v12
	v_add_u32_e32 v11, v11, v1
	v_and_or_b32 v22, v11, s28, v12
	v_add_u32_e32 v11, v11, v1
	v_and_or_b32 v23, v11, s28, v12
	v_add_u32_e32 v11, v11, v1
	v_and_or_b32 v24, v11, s28, v12
	v_add_u32_e32 v11, v11, v1
	v_and_or_b32 v25, v11, s28, v12
	v_add_u32_e32 v11, v11, v1
	v_and_or_b32 v28, v11, s28, v12
	v_add_u32_e32 v11, v11, v1
	v_and_or_b32 v29, v11, s28, v12
	v_add_u32_e32 v11, v11, v1
	v_and_or_b32 v30, v11, s28, v12
	v_add_u32_e32 v11, v11, v1
	ds_read_b32 v21, v21
	ds_read_b32 v22, v22
	ds_read_b32 v23, v23
	ds_read_b32 v24, v24
	ds_read_b32 v25, v25
	ds_read_b32 v28, v28
	ds_read_b32 v29, v29
	ds_read_b32 v30, v30
	s_waitcnt lgkmcnt(8)
; __device__ __forceinline__ void phase0(const Params& p, LAS unsigned char* lds) {
;     ...
;     for (int i = gt; i < 4 * 128 * 256; i += NGT) {
;         const int k = i & 255, e = (i >> 8) & 127, g = i >> 15, d = k & 127; const bool sn = k >= 128;
;         float s = 0.f;
;         for (int dp = 0; dp < 128; ++dp) { const float fr = (float)((d * dp) & 127) * (1.f / 128.f);
;             const float tw = sn ? __builtin_amdgcn_sinf(fr) : __builtin_amdgcn_cosf(fr);
;             s += tw * wf[(g * 128 + dp) * 128 + e]; }
;         CWT[i] = (h16)(s * 0.08838834764831845f);
	v_readlane_b32 s9, v27, 0
	v_fmac_f32_e32 v10, s9, v13
	v_readlane_b32 s12, v27, 1
	v_fmac_f32_e32 v10, s12, v14
	v_readlane_b32 s9, v27, 2
	v_fmac_f32_e32 v10, s9, v15
	v_readlane_b32 s12, v27, 3
	v_fmac_f32_e32 v10, s12, v16
	v_readlane_b32 s9, v27, 4
	v_fmac_f32_e32 v10, s9, v17
	v_readlane_b32 s12, v27, 5
	v_fmac_f32_e32 v10, s12, v18
	v_readlane_b32 s9, v27, 6
	v_fmac_f32_e32 v10, s9, v19
	v_readlane_b32 s12, v27, 7
	v_fmac_f32_e32 v10, s12, v20
	v_and_or_b32 v13, v11, s28, v12
	v_add_u32_e32 v11, v11, v1
	v_and_or_b32 v14, v11, s28, v12
	v_add_u32_e32 v11, v11, v1
	v_and_or_b32 v15, v11, s28, v12
	v_add_u32_e32 v11, v11, v1
	v_and_or_b32 v16, v11, s28, v12
	v_add_u32_e32 v11, v11, v1
	v_and_or_b32 v17, v11, s28, v12
	v_add_u32_e32 v11, v11, v1
	v_and_or_b32 v18, v11, s28, v12
	v_add_u32_e32 v11, v11, v1
	v_and_or_b32 v19, v11, s28, v12
	v_add_u32_e32 v11, v11, v1
	v_and_or_b32 v20, v11, s28, v12
	v_add_u32_e32 v11, v11, v1
	ds_read_b32 v13, v13
	ds_read_b32 v14, v14
	ds_read_b32 v15, v15
	ds_read_b32 v16, v16
	ds_read_b32 v17, v17
	ds_read_b32 v18, v18
	ds_read_b32 v19, v19
	ds_read_b32 v20, v20
	s_waitcnt lgkmcnt(8)
	v_readlane_b32 s9, v27, 8
	v_fmac_f32_e32 v10, s9, v21
	v_readlane_b32 s12, v27, 9
	v_fmac_f32_e32 v10, s12, v22
	v_readlane_b32 s9, v27, 10
	v_fmac_f32_e32 v10, s9, v23
	v_readlane_b32 s12, v27, 11
	v_fmac_f32_e32 v10, s12, v24
	v_readlane_b32 s9, v27, 12
	v_fmac_f32_e32 v10, s9, v25
	v_readlane_b32 s12, v27, 13
	v_fmac_f32_e32 v10, s12, v28
	v_readlane_b32 s9, v27, 14
	v_fmac_f32_e32 v10, s9, v29
	v_readlane_b32 s12, v27, 15
	v_fmac_f32_e32 v10, s12, v30
	v_and_or_b32 v21, v11, s28, v12
	v_add_u32_e32 v11, v11, v1
	v_and_or_b32 v22, v11, s28, v12
	v_add_u32_e32 v11, v11, v1
	v_and_or_b32 v23, v11, s28, v12
	v_add_u32_e32 v11, v11, v1
	v_and_or_b32 v24, v11, s28, v12
	v_add_u32_e32 v11, v11, v1
	v_and_or_b32 v25, v11, s28, v12
	v_add_u32_e32 v11, v11, v1
	v_and_or_b32 v28, v11, s28, v12
	v_add_u32_e32 v11, v11, v1
	v_and_or_b32 v29, v11, s28, v12
	v_add_u32_e32 v11, v11, v1
	v_and_or_b32 v30, v11, s28, v12
	v_add_u32_e32 v11, v11, v1
	ds_read_b32 v21, v21
	ds_read_b32 v22, v22
	ds_read_b32 v23, v23
	ds_read_b32 v24, v24
	ds_read_b32 v25, v25
	ds_read_b32 v28, v28
	ds_read_b32 v29, v29
	ds_read_b32 v30, v30
	s_waitcnt lgkmcnt(8)
	v_readlane_b32 s9, v27, 16
	v_fmac_f32_e32 v10, s9, v13
	v_readlane_b32 s12, v27, 17
	v_fmac_f32_e32 v10, s12, v14
	v_readlane_b32 s9, v27, 18
	v_fmac_f32_e32 v10, s9, v15
	v_readlane_b32 s12, v27, 19
	v_fmac_f32_e32 v10, s12, v16
	v_readlane_b32 s9, v27, 20
	v_fmac_f32_e32 v10, s9, v17
	v_readlane_b32 s12, v27, 21
	v_fmac_f32_e32 v10, s12, v18
	v_readlane_b32 s9, v27, 22
	v_fmac_f32_e32 v10, s9, v19
	v_readlane_b32 s12, v27, 23
	v_fmac_f32_e32 v10, s12, v20
	v_and_or_b32 v13, v11, s28, v12
	v_add_u32_e32 v11, v11, v1
	v_and_or_b32 v14, v11, s28, v12
	v_add_u32_e32 v11, v11, v1
	v_and_or_b32 v15, v11, s28, v12
	v_add_u32_e32 v11, v11, v1
	v_and_or_b32 v16, v11, s28, v12
	v_add_u32_e32 v11, v11, v1
	v_and_or_b32 v17, v11, s28, v12
	v_add_u32_e32 v11, v11, v1
	v_and_or_b32 v18, v11, s28, v12
	v_add_u32_e32 v11, v11, v1
	v_and_or_b32 v19, v11, s28, v12
	v_add_u32_e32 v11, v11, v1
	v_and_or_b32 v20, v11, s28, v12
	v_add_u32_e32 v11, v11, v1
	ds_read_b32 v13, v13
	ds_read_b32 v14, v14
	ds_read_b32 v15, v15
	ds_read_b32 v16, v16
	ds_read_b32 v17, v17
	ds_read_b32 v18, v18
	ds_read_b32 v19, v19
	ds_read_b32 v20, v20
	s_waitcnt lgkmcnt(8)
	v_readlane_b32 s9, v27, 24
	v_fmac_f32_e32 v10, s9, v21
	v_readlane_b32 s12, v27, 25
	v_fmac_f32_e32 v10, s12, v22
	v_readlane_b32 s9, v27, 26
	v_fmac_f32_e32 v10, s9, v23
	v_readlane_b32 s12, v27, 27
	v_fmac_f32_e32 v10, s12, v24
	v_readlane_b32 s9, v27, 28
	v_fmac_f32_e32 v10, s9, v25
	v_readlane_b32 s12, v27, 29
	v_fmac_f32_e32 v10, s12, v28
	v_readlane_b32 s9, v27, 30
	v_fmac_f32_e32 v10, s9, v29
	v_readlane_b32 s12, v27, 31
	v_fmac_f32_e32 v10, s12, v30
	v_and_or_b32 v21, v11, s28, v12
	v_add_u32_e32 v11, v11, v1
	v_and_or_b32 v22, v11, s28, v12
	v_add_u32_e32 v11, v11, v1
	v_and_or_b32 v23, v11, s28, v12
	v_add_u32_e32 v11, v11, v1
	v_and_or_b32 v24, v11, s28, v12
	v_add_u32_e32 v11, v11, v1
	v_and_or_b32 v25, v11, s28, v12
	v_add_u32_e32 v11, v11, v1
	v_and_or_b32 v28, v11, s28, v12
	v_add_u32_e32 v11, v11, v1
	v_and_or_b32 v29, v11, s28, v12
	v_add_u32_e32 v11, v11, v1
	v_and_or_b32 v30, v11, s28, v12
	v_add_u32_e32 v11, v11, v1
	ds_read_b32 v21, v21
	ds_read_b32 v22, v22
	ds_read_b32 v23, v23
	ds_read_b32 v24, v24
	ds_read_b32 v25, v25
	ds_read_b32 v28, v28
	ds_read_b32 v29, v29
	ds_read_b32 v30, v30
	s_waitcnt lgkmcnt(8)
; __device__ __forceinline__ void phase0(const Params& p, LAS unsigned char* lds) {
;     ...
;     for (int i = gt; i < 4 * 128 * 256; i += NGT) {
;         const int k = i & 255, e = (i >> 8) & 127, g = i >> 15, d = k & 127; const bool sn = k >= 128;
;         float s = 0.f;
;         for (int dp = 0; dp < 128; ++dp) { const float fr = (float)((d * dp) & 127) * (1.f / 128.f);
;             const float tw = sn ? __builtin_amdgcn_sinf(fr) : __builtin_amdgcn_cosf(fr);
;             s += tw * wf[(g * 128 + dp) * 128 + e]; }
;         CWT[i] = (h16)(s * 0.08838834764831845f);
	v_readlane_b32 s9, v27, 32
	v_fmac_f32_e32 v10, s9, v13
	v_readlane_b32 s12, v27, 33
	v_fmac_f32_e32 v10, s12, v14
	v_readlane_b32 s9, v27, 34
	v_fmac_f32_e32 v10, s9, v15
	v_readlane_b32 s12, v27, 35
	v_fmac_f32_e32 v10, s12, v16
	v_readlane_b32 s9, v27, 36
	v_fmac_f32_e32 v10, s9, v17
	v_readlane_b32 s12, v27, 37
	v_fmac_f32_e32 v10, s12, v18
	v_readlane_b32 s9, v27, 38
	v_fmac_f32_e32 v10, s9, v19
	v_readlane_b32 s12, v27, 39
	v_fmac_f32_e32 v10, s12, v20
	v_and_or_b32 v13, v11, s28, v12
	v_add_u32_e32 v11, v11, v1
	v_and_or_b32 v14, v11, s28, v12
	v_add_u32_e32 v11, v11, v1
	v_and_or_b32 v15, v11, s28, v12
	v_add_u32_e32 v11, v11, v1
	v_and_or_b32 v16, v11, s28, v12
	v_add_u32_e32 v11, v11, v1
	v_and_or_b32 v17, v11, s28, v12
	v_add_u32_e32 v11, v11, v1
	v_and_or_b32 v18, v11, s28, v12
	v_add_u32_e32 v11, v11, v1
	v_and_or_b32 v19, v11, s28, v12
	v_add_u32_e32 v11, v11, v1
	v_and_or_b32 v20, v11, s28, v12
	v_add_u32_e32 v11, v11, v1
	ds_read_b32 v13, v13
	ds_read_b32 v14, v14
	ds_read_b32 v15, v15
	ds_read_b32 v16, v16
	ds_read_b32 v17, v17
	ds_read_b32 v18, v18
	ds_read_b32 v19, v19
	ds_read_b32 v20, v20
	s_waitcnt lgkmcnt(8)
	v_readlane_b32 s9, v27, 40
	v_fmac_f32_e32 v10, s9, v21
	v_readlane_b32 s12, v27, 41
	v_fmac_f32_e32 v10, s12, v22
	v_readlane_b32 s9, v27, 42
	v_fmac_f32_e32 v10, s9, v23
	v_readlane_b32 s12, v27, 43
	v_fmac_f32_e32 v10, s12, v24
	v_readlane_b32 s9, v27, 44
	v_fmac_f32_e32 v10, s9, v25
	v_readlane_b32 s12, v27, 45
	v_fmac_f32_e32 v10, s12, v28
	v_readlane_b32 s9, v27, 46
	v_fmac_f32_e32 v10, s9, v29
	v_readlane_b32 s12, v27, 47
	v_fmac_f32_e32 v10, s12, v30
	v_and_or_b32 v21, v11, s28, v12
	v_add_u32_e32 v11, v11, v1
	v_and_or_b32 v22, v11, s28, v12
	v_add_u32_e32 v11, v11, v1
	v_and_or_b32 v23, v11, s28, v12
	v_add_u32_e32 v11, v11, v1
	v_and_or_b32 v24, v11, s28, v12
	v_add_u32_e32 v11, v11, v1
	v_and_or_b32 v25, v11, s28, v12
	v_add_u32_e32 v11, v11, v1
	v_and_or_b32 v28, v11, s28, v12
	v_add_u32_e32 v11, v11, v1
	v_and_or_b32 v29, v11, s28, v12
	v_add_u32_e32 v11, v11, v1
	v_and_or_b32 v30, v11, s28, v12
	v_add_u32_e32 v11, v11, v1
	ds_read_b32 v21, v21
	ds_read_b32 v22, v22
	ds_read_b32 v23, v23
	ds_read_b32 v24, v24
	ds_read_b32 v25, v25
	ds_read_b32 v28, v28
	ds_read_b32 v29, v29
	ds_read_b32 v30, v30
	s_waitcnt lgkmcnt(8)
	v_readlane_b32 s9, v27, 48
	v_fmac_f32_e32 v10, s9, v13
	v_readlane_b32 s12, v27, 49
	v_fmac_f32_e32 v10, s12, v14
	v_readlane_b32 s9, v27, 50
	v_fmac_f32_e32 v10, s9, v15
	v_readlane_b32 s12, v27, 51
	v_fmac_f32_e32 v10, s12, v16
	v_readlane_b32 s9, v27, 52
	v_fmac_f32_e32 v10, s9, v17
	v_readlane_b32 s12, v27, 53
	v_fmac_f32_e32 v10, s12, v18
	v_readlane_b32 s9, v27, 54
	v_fmac_f32_e32 v10, s9, v19
	v_readlane_b32 s12, v27, 55
	v_fmac_f32_e32 v10, s12, v20
	s_waitcnt lgkmcnt(0)
	v_readlane_b32 s9, v27, 56
	v_fmac_f32_e32 v10, s9, v21
	v_readlane_b32 s12, v27, 57
	v_fmac_f32_e32 v10, s12, v22
	v_readlane_b32 s9, v27, 58
	v_fmac_f32_e32 v10, s9, v23
	v_readlane_b32 s12, v27, 59
	v_fmac_f32_e32 v10, s12, v24
	v_readlane_b32 s9, v27, 60
	v_fmac_f32_e32 v10, s9, v25
	v_readlane_b32 s12, v27, 61
	v_fmac_f32_e32 v10, s12, v28
	v_readlane_b32 s9, v27, 62
	v_fmac_f32_e32 v10, s9, v29
	v_readlane_b32 s12, v27, 63
	v_fmac_f32_e32 v10, s12, v30
	v_ashrrev_i32_e32 v1, 31, v0
	v_fma_mixlo_f16 v9, v10, s20, 0
	v_lshl_add_u64 v[10:11], v[0:1], 1, s[4:5]
	v_add_u32_e32 v0, s8, v0
	v_cmp_lt_i32_e32 vcc, s21, v0
	s_or_b64 s[10:11], vcc, s[10:11]
	global_store_short v[10:11], v9, off
	s_andn2_b64 exec, exec, s[10:11]
	s_cbranch_execnz .LBB0_126
